# row passes (E1, E3, E5, prologue x-convert): first four butterfly steps of each wave sum done with DPP adds instead of ds_bpermute round trips
# baseline (speedup 1.0000x reference)
; __device__ __forceinline__ void unpack8(const u32x4 w, float (&f)[8]) { f[0] = bflo(w.x); f[1] = bfhi(w.x); f[2] = bflo(w.y); f[3] = bfhi(w.y); f[4] = bflo(w.z); f[5] = bfhi(w.z); f[6] = bflo(w.w); f[7] = bfhi(w.w); }
; __device__ __forceinline__ u32x4 pack8(const float (&f)[8]) { u32x4 w; w.x = pkbf(f[0], f[1]); w.y = pkbf(f[2], f[3]); w.z = pkbf(f[4], f[5]); w.w = pkbf(f[6], f[7]); return w; }
; #define RN_LOAD(dy, dx, rbase) do { _Pragma("unroll") for (int i = 0; i < 2; ++i) { int r_ = (rbase) + i * NGW; if (r_ >= M) r_ = (rbase) < M ? (rbase) : gw; \
;         _Pragma("unroll") for (int q = 0; q < 2; ++q) { const int c8 = 8 * (lane + 64 * q); dy[i][q] = *(const u32x4*)(yb + (size_t)r_ * 1024 + c8); dx[i][q] = *(const u32x4*)(xbin + (size_t)r_ * 1024 + c8); } } } while (0)
; __device__ __forceinline__ void resnorm_pass(const float* xa, const float* xs, const bf16_t* xbin, const bf16_t* yb, const float* g, bf16_t* xb, float* ss_out, float* ss_zero, int gw, int NGW, int lane) {
;     ...
;     RN_LOAD(yw, xw, gw);
;     for (int r0 = gw; r0 < M; r0 += 2 * NGW) {
;         RN_LOAD(yn, xn, r0 + 2 * NGW);
; #pragma unroll
;         for (int i = 0; i < 2; ++i) { const int r = r0 + i * NGW; const bool ok = r < M; float y[2][8], x[2][8]; float s2 = 0.f;
; #pragma unroll
;             for (int q = 0; q < 2; ++q) { unpack8(yw[i][q], y[q]); unpack8(xw[i][q], x[q]);
; #pragma unroll
;                 for (int j = 0; j < 8; ++j) s2 += y[q][j] * y[q][j]; }
;             s2 = wave_sum(s2); const float rs = rsqrtf(s2 * (1.0f / 1024.0f) + EPS); float s3 = 0.f;
; #pragma unroll
;             for (int q = 0; q < 2; ++q) { float o[8];
; #pragma unroll
;                 for (int j = 0; j < 4; ++j) { o[j] = x[q][j] + y[q][j] * rs * gv[q][0][j]; o[4 + j] = x[q][4 + j] + y[q][4 + j] * rs * gv[q][1][j]; }
;                 const u32x4 w = pack8(o);
;                 if (ss_out) { float ob[8]; unpack8(w, ob);
; #pragma unroll
;                     for (int j = 0; j < 8; ++j) s3 += ob[j] * ob[j]; }
;                 if (ok) *(u32x4*)(xb + (size_t)r * 1024 + 8 * (lane + 64 * q)) = w; }
.LBB0_20:
	s_add_i32 s22, s3, s12
	s_cmp_lt_i32 s22, 0x10100
	s_cselect_b32 s24, s22, s92
	s_cmp_gt_i32 s22, 0x100ff
	s_cselect_b32 s22, s92, s22
	s_ashr_i32 s23, s22, 31
	s_waitcnt vmcnt(0)
	v_mov_b64_e32 v[88:89], v[18:19]
	s_lshl_b64 s[22:23], s[22:23], 11
	v_mov_b64_e32 v[86:87], v[16:17]
	v_lshl_add_u64 v[16:17], v[64:65], 0, s[22:23]
	v_lshl_add_u64 v[18:19], v[66:67], 0, s[22:23]
	s_add_i32 s22, s1, s12
	s_cmp_gt_i32 s22, 0x100ff
	s_cselect_b32 s22, s24, s22
	s_ashr_i32 s23, s22, 31
	s_lshl_b64 s[22:23], s[22:23], 11
	s_waitcnt vmcnt(1)
	v_mov_b64_e32 v[72:73], v[34:35]
	s_waitcnt vmcnt(0)
	v_mov_b64_e32 v[76:77], v[30:31]
	v_mov_b64_e32 v[92:93], v[22:23]
	v_lshl_add_u64 v[44:45], v[64:65], 0, s[22:23]
	v_lshl_add_u64 v[52:53], v[66:67], 0, s[22:23]
	v_mov_b64_e32 v[70:71], v[32:33]
	v_mov_b64_e32 v[74:75], v[28:29]
	v_mov_b64_e32 v[90:91], v[20:21]
	global_load_dwordx4 v[28:31], v[16:17], off
	global_load_dwordx4 v[32:35], v[16:17], off offset:1024
	global_load_dwordx4 v[20:23], v[18:19], off
	s_nop 0
	global_load_dwordx4 v[16:19], v[18:19], off offset:1024
	s_nop 0
	global_load_dwordx4 v[40:43], v[44:45], off
	s_nop 0
	global_load_dwordx4 v[44:47], v[44:45], off offset:1024
	s_nop 0
	global_load_dwordx4 v[48:51], v[52:53], off
	s_nop 0
	global_load_dwordx4 v[52:55], v[52:53], off offset:1024
	v_lshlrev_b32_e32 v102, 16, v74
	v_and_b32_e32 v103, 0xffff0000, v74
	v_lshlrev_b32_e32 v98, 16, v75
	v_and_b32_e32 v99, 0xffff0000, v75
	v_pk_mul_f32 v[74:75], v[102:103], v[102:103]
	v_pk_mul_f32 v[100:101], v[98:99], v[98:99]
	v_add_f32_e32 v74, v74, v75
	v_lshlrev_b32_e32 v96, 16, v76
	v_and_b32_e32 v97, 0xffff0000, v76
	v_add_f32_e32 v74, v100, v74
	v_lshlrev_b32_e32 v78, 16, v77
	v_and_b32_e32 v79, 0xffff0000, v77
	v_pk_mul_f32 v[76:77], v[96:97], v[96:97]
	v_add_f32_e32 v74, v101, v74
	v_add_f32_e32 v74, v76, v74
	v_pk_mul_f32 v[94:95], v[78:79], v[78:79]
	v_add_f32_e32 v74, v77, v74
	v_lshlrev_b32_e32 v114, 16, v70
	v_and_b32_e32 v115, 0xffff0000, v70
	v_add_f32_e32 v74, v94, v74
	v_lshlrev_b32_e32 v110, 16, v71
	v_and_b32_e32 v111, 0xffff0000, v71
	v_pk_mul_f32 v[70:71], v[114:115], v[114:115]
	v_add_f32_e32 v74, v95, v74
	v_add_f32_e32 v70, v70, v74
	v_pk_mul_f32 v[112:113], v[110:111], v[110:111]
	v_add_f32_e32 v70, v71, v70
	v_lshlrev_b32_e32 v108, 16, v72
	v_and_b32_e32 v109, 0xffff0000, v72
	v_add_f32_e32 v70, v112, v70
	v_lshlrev_b32_e32 v104, 16, v73
	v_and_b32_e32 v105, 0xffff0000, v73
	v_pk_mul_f32 v[72:73], v[108:109], v[108:109]
	v_add_f32_e32 v70, v113, v70
	v_add_f32_e32 v70, v72, v70
	v_pk_mul_f32 v[106:107], v[104:105], v[104:105]
	v_add_f32_e32 v70, v73, v70
	v_add_f32_e32 v70, v106, v70
	v_add_f32_e32 v70, v107, v70
	v_and_b32_e32 v73, 0xffff0000, v92
	v_lshlrev_b32_e32 v74, 16, v91
	v_and_b32_e32 v77, 0xffff0000, v90
	s_waitcnt lgkmcnt(0)
	s_nop 1
	v_add_f32_dpp v70, v70, v70 quad_perm:[1,0,3,2] row_mask:0xf bank_mask:0xf
	s_waitcnt lgkmcnt(0)
	s_nop 1
	v_add_f32_dpp v71, v70, v70 quad_perm:[2,3,0,1] row_mask:0xf bank_mask:0xf
	v_lshlrev_b32_e32 v70, 16, v93
	s_waitcnt lgkmcnt(0)
	s_nop 1
	v_add_f32_dpp v75, v71, v71 row_half_mirror row_mask:0xf bank_mask:0xf
	v_lshlrev_b32_e32 v72, 16, v92
	v_and_b32_e32 v71, 0xffff0000, v93
	s_waitcnt lgkmcnt(0)
	s_nop 1
	v_add_f32_dpp v92, v75, v75 row_mirror row_mask:0xf bank_mask:0xf
	ds_bpermute_b32 v93, v84, v92
	v_and_b32_e32 v75, 0xffff0000, v91
	v_lshlrev_b32_e32 v76, 16, v90
	v_lshlrev_b32_e32 v90, 16, v89
	v_and_b32_e32 v91, 0xffff0000, v89
	s_waitcnt lgkmcnt(0)
	v_add_f32_e32 v94, v92, v93
	ds_bpermute_b32 v95, v85, v94
	v_lshlrev_b32_e32 v92, 16, v88
	v_and_b32_e32 v93, 0xffff0000, v88
	v_lshlrev_b32_e32 v88, 16, v87
	s_waitcnt lgkmcnt(0)
	v_add_f32_e32 v89, v94, v95
	v_fmamk_f32 v89, v89, 0x3a800000, v134
	v_mul_f32_e32 v94, 0x4b800000, v89
	v_cmp_gt_f32_e64 s[40:41], s13, v89
	v_and_b32_e32 v95, 0xffff0000, v86
	s_nop 0
	v_cndmask_b32_e64 v89, v89, v94, s[40:41]
	v_rsq_f32_e32 v100, v89
	v_lshlrev_b32_e32 v94, 16, v86
	v_and_b32_e32 v89, 0xffff0000, v87
	v_mul_f32_e32 v86, 0x45800000, v100
	v_cndmask_b32_e64 v86, v100, v86, s[40:41]
	v_pk_mul_f32 v[96:97], v[86:87], v[96:97] op_sel_hi:[0,1]
	v_pk_mul_f32 v[100:101], v[86:87], v[102:103] op_sel_hi:[0,1]
	v_pk_fma_f32 v[72:73], v[12:13], v[96:97], v[72:73]
	v_pk_mul_f32 v[96:97], v[86:87], v[98:99] op_sel_hi:[0,1]
	v_pk_mul_f32 v[78:79], v[86:87], v[78:79] op_sel_hi:[0,1]
	v_pk_fma_f32 v[76:77], v[8:9], v[100:101], v[76:77]
	v_pk_fma_f32 v[74:75], v[10:11], v[96:97], v[74:75]
	v_pk_fma_f32 v[78:79], v[14:15], v[78:79], v[70:71]
	v_cvt_pk_bf16_f32 v70, v76, v77
	v_cvt_pk_bf16_f32 v71, v74, v75
	v_cvt_pk_bf16_f32 v72, v72, v73
	v_cvt_pk_bf16_f32 v73, v78, v79
	global_store_dwordx4 v[68:69], v[70:73], off
	v_pk_mul_f32 v[74:75], v[86:87], v[110:111] op_sel_hi:[0,1]
	v_pk_mul_f32 v[76:77], v[86:87], v[104:105] op_sel_hi:[0,1]
	v_pk_mul_f32 v[70:71], v[86:87], v[114:115] op_sel_hi:[0,1]
	v_pk_mul_f32 v[72:73], v[86:87], v[108:109] op_sel_hi:[0,1]
	v_pk_fma_f32 v[70:71], v[0:1], v[70:71], v[94:95]
	v_pk_fma_f32 v[72:73], v[4:5], v[72:73], v[92:93]
	v_pk_fma_f32 v[74:75], v[2:3], v[74:75], v[88:89]
	v_pk_fma_f32 v[76:77], v[6:7], v[76:77], v[90:91]
	v_cvt_pk_bf16_f32 v70, v70, v71
	v_cvt_pk_bf16_f32 v71, v74, v75
	v_cvt_pk_bf16_f32 v72, v72, v73
	v_cvt_pk_bf16_f32 v73, v76, v77
	global_store_dwordx4 v[68:69], v[70:73], off offset:1024
	s_and_saveexec_b64 s[40:41], vcc
	s_cbranch_execz .LBB0_22
	global_store_dword v133, v133, s[4:5]
; __device__ __forceinline__ void unpack8(const u32x4 w, float (&f)[8]) { f[0] = bflo(w.x); f[1] = bfhi(w.x); f[2] = bflo(w.y); f[3] = bfhi(w.y); f[4] = bflo(w.z); f[5] = bfhi(w.z); f[6] = bflo(w.w); f[7] = bfhi(w.w); }
; __device__ __forceinline__ u32x4 pack8(const float (&f)[8]) { u32x4 w; w.x = pkbf(f[0], f[1]); w.y = pkbf(f[2], f[3]); w.z = pkbf(f[4], f[5]); w.w = pkbf(f[6], f[7]); return w; }
; __device__ __forceinline__ void resnorm_pass(const float* xa, const float* xs, const bf16_t* xbin, const bf16_t* yb, const float* g, bf16_t* xb, float* ss_out, float* ss_zero, int gw, int NGW, int lane) {
;     ...
;         for (int i = 0; i < 2; ++i) { const int r = r0 + i * NGW; const bool ok = r < M; float y[2][8], x[2][8]; float s2 = 0.f;
; #pragma unroll
;             for (int q = 0; q < 2; ++q) { unpack8(yw[i][q], y[q]); unpack8(xw[i][q], x[q]);
; #pragma unroll
;                 for (int j = 0; j < 8; ++j) s2 += y[q][j] * y[q][j]; }
;             s2 = wave_sum(s2); const float rs = rsqrtf(s2 * (1.0f / 1024.0f) + EPS); float s3 = 0.f;
; #pragma unroll
;             for (int q = 0; q < 2; ++q) { float o[8];
; #pragma unroll
;                 for (int j = 0; j < 4; ++j) { o[j] = x[q][j] + y[q][j] * rs * gv[q][0][j]; o[4 + j] = x[q][4 + j] + y[q][4 + j] * rs * gv[q][1][j]; }
;                 const u32x4 w = pack8(o);
;                 if (ss_out) { float ob[8]; unpack8(w, ob);
; #pragma unroll
;                     for (int j = 0; j < 8; ++j) s3 += ob[j] * ob[j]; }
;                 if (ok) *(u32x4*)(xb + (size_t)r * 1024 + 8 * (lane + 64 * q)) = w; }
.LBB0_22:
	s_or_b64 exec, exec, s[40:41]
	v_lshlrev_b32_e32 v78, 16, v60
	v_and_b32_e32 v79, 0xffff0000, v60
	v_lshlrev_b32_e32 v76, 16, v61
	v_and_b32_e32 v77, 0xffff0000, v61
	v_pk_mul_f32 v[86:87], v[78:79], v[78:79]
	v_pk_mul_f32 v[88:89], v[76:77], v[76:77]
	v_add_f32_e32 v86, v86, v87
	v_lshlrev_b32_e32 v74, 16, v62
	v_and_b32_e32 v75, 0xffff0000, v62
	v_add_f32_e32 v86, v88, v86
	v_pk_mul_f32 v[90:91], v[74:75], v[74:75]
	v_add_f32_e32 v86, v89, v86
	v_lshlrev_b32_e32 v72, 16, v63
	v_and_b32_e32 v73, 0xffff0000, v63
	v_add_f32_e32 v86, v90, v86
	v_pk_mul_f32 v[92:93], v[72:73], v[72:73]
	v_add_f32_e32 v86, v91, v86
	v_lshlrev_b32_e32 v70, 16, v56
	v_and_b32_e32 v71, 0xffff0000, v56
	v_add_f32_e32 v86, v92, v86
	v_lshlrev_b32_e32 v62, 16, v57
	v_and_b32_e32 v63, 0xffff0000, v57
	v_lshlrev_b32_e32 v60, 16, v58
	v_and_b32_e32 v61, 0xffff0000, v58
	v_lshlrev_b32_e32 v56, 16, v59
	v_and_b32_e32 v57, 0xffff0000, v59
	v_pk_mul_f32 v[58:59], v[70:71], v[70:71]
	v_add_f32_e32 v86, v93, v86
	v_add_f32_e32 v58, v58, v86
	v_pk_mul_f32 v[94:95], v[62:63], v[62:63]
	v_add_f32_e32 v58, v59, v58
	v_add_f32_e32 v58, v94, v58
	v_pk_mul_f32 v[96:97], v[60:61], v[60:61]
	v_add_f32_e32 v58, v95, v58
	v_add_f32_e32 v58, v96, v58
	v_pk_mul_f32 v[98:99], v[56:57], v[56:57]
	v_add_f32_e32 v58, v97, v58
	v_add_f32_e32 v58, v98, v58
	v_add_f32_e32 v58, v99, v58
	s_add_i32 s46, s0, s12
	s_cmp_lt_i32 s46, 0x10100
	s_cselect_b64 s[48:49], -1, 0
	s_ashr_i32 s47, s46, 31
	s_waitcnt lgkmcnt(0)
	s_nop 1
	v_add_f32_dpp v58, v58, v58 quad_perm:[1,0,3,2] row_mask:0xf bank_mask:0xf
	s_cmp_gt_i32 s46, 0x100ff
	s_waitcnt lgkmcnt(0)
	s_nop 1
	v_add_f32_dpp v58, v58, v58 quad_perm:[2,3,0,1] row_mask:0xf bank_mask:0xf
	s_waitcnt lgkmcnt(0)
	s_nop 1
	v_add_f32_dpp v58, v58, v58 row_half_mirror row_mask:0xf bank_mask:0xf
	s_waitcnt lgkmcnt(0)
	s_nop 1
	v_add_f32_dpp v58, v58, v58 row_mirror row_mask:0xf bank_mask:0xf
	ds_bpermute_b32 v59, v84, v58
	s_waitcnt lgkmcnt(0)
	v_add_f32_e32 v58, v58, v59
	ds_bpermute_b32 v59, v85, v58
	s_cbranch_scc1 .LBB0_24
	s_waitcnt lgkmcnt(0)
	v_add_f32_e32 v58, v58, v59
	v_fmamk_f32 v58, v58, 0x3a800000, v134
	v_mul_f32_e32 v59, 0x4b800000, v58
	v_cmp_gt_f32_e64 s[40:41], s13, v58
	v_lshlrev_b32_e32 v88, 16, v36
	v_and_b32_e32 v89, 0xffff0000, v36
	v_cndmask_b32_e64 v58, v58, v59, s[40:41]
	v_rsq_f32_e32 v86, v58
	s_lshl_b64 s[22:23], s[46:47], 11
	v_lshl_add_u64 v[58:59], v[66:67], 0, s[22:23]
	v_mul_f32_e32 v87, 0x45800000, v86
	v_cndmask_b32_e64 v86, v86, v87, s[40:41]
	v_pk_mul_f32 v[78:79], v[86:87], v[78:79] op_sel_hi:[0,1]
	v_pk_fma_f32 v[78:79], v[8:9], v[78:79], v[88:89]
	v_pk_mul_f32 v[76:77], v[86:87], v[76:77] op_sel_hi:[0,1]
	v_cvt_pk_bf16_f32 v36, v78, v79
	v_lshlrev_b32_e32 v78, 16, v37
	v_and_b32_e32 v79, 0xffff0000, v37
	v_pk_fma_f32 v[76:77], v[10:11], v[76:77], v[78:79]
	v_pk_mul_f32 v[74:75], v[86:87], v[74:75] op_sel_hi:[0,1]
	v_cvt_pk_bf16_f32 v37, v76, v77
	v_lshlrev_b32_e32 v76, 16, v38
	v_and_b32_e32 v77, 0xffff0000, v38
	v_pk_fma_f32 v[74:75], v[12:13], v[74:75], v[76:77]
	v_pk_mul_f32 v[72:73], v[86:87], v[72:73] op_sel_hi:[0,1]
	v_cvt_pk_bf16_f32 v38, v74, v75
	v_lshlrev_b32_e32 v74, 16, v39
	v_and_b32_e32 v75, 0xffff0000, v39
	v_pk_fma_f32 v[72:73], v[14:15], v[72:73], v[74:75]
	s_nop 0
	v_cvt_pk_bf16_f32 v39, v72, v73
	global_store_dwordx4 v[58:59], v[36:39], off
	s_nop 1
	v_lshlrev_b32_e32 v36, 16, v24
	v_and_b32_e32 v37, 0xffff0000, v24
	v_pk_mul_f32 v[38:39], v[86:87], v[70:71] op_sel_hi:[0,1]
	v_pk_fma_f32 v[36:37], v[0:1], v[38:39], v[36:37]
	v_pk_mul_f32 v[38:39], v[86:87], v[62:63] op_sel_hi:[0,1]
	v_cvt_pk_bf16_f32 v24, v36, v37
	v_lshlrev_b32_e32 v36, 16, v25
	v_and_b32_e32 v37, 0xffff0000, v25
	v_pk_fma_f32 v[36:37], v[2:3], v[38:39], v[36:37]
	v_pk_mul_f32 v[38:39], v[86:87], v[60:61] op_sel_hi:[0,1]
	v_cvt_pk_bf16_f32 v25, v36, v37
	v_lshlrev_b32_e32 v36, 16, v26
	v_and_b32_e32 v37, 0xffff0000, v26
	v_pk_fma_f32 v[36:37], v[4:5], v[38:39], v[36:37]
	v_pk_mul_f32 v[38:39], v[86:87], v[56:57] op_sel_hi:[0,1]
	v_cvt_pk_bf16_f32 v26, v36, v37
	v_lshlrev_b32_e32 v36, 16, v27
	v_and_b32_e32 v37, 0xffff0000, v27
	v_pk_fma_f32 v[36:37], v[6:7], v[38:39], v[36:37]
	s_nop 0
	v_cvt_pk_bf16_f32 v27, v36, v37
	global_store_dwordx4 v[58:59], v[24:27], off offset:1024

; __device__ __forceinline__ void unpack8(const u32x4 w, float (&f)[8]) { f[0] = bflo(w.x); f[1] = bfhi(w.x); f[2] = bflo(w.y); f[3] = bfhi(w.y); f[4] = bflo(w.z); f[5] = bfhi(w.z); f[6] = bflo(w.w); f[7] = bfhi(w.w); }
; __device__ __forceinline__ u32x4 pack8(const float (&f)[8]) { u32x4 w; w.x = pkbf(f[0], f[1]); w.y = pkbf(f[2], f[3]); w.z = pkbf(f[4], f[5]); w.w = pkbf(f[6], f[7]); return w; }
; #define RN_LOAD(dy, dx, rbase) do { _Pragma("unroll") for (int i = 0; i < 2; ++i) { int r_ = (rbase) + i * NGW; if (r_ >= M) r_ = (rbase) < M ? (rbase) : gw; \
;         _Pragma("unroll") for (int q = 0; q < 2; ++q) { const int c8 = 8 * (lane + 64 * q); dy[i][q] = *(const u32x4*)(yb + (size_t)r_ * 1024 + c8); dx[i][q] = *(const u32x4*)(xbin + (size_t)r_ * 1024 + c8); } } } while (0)
; __device__ __forceinline__ void resnorm_pass(const float* xa, const float* xs, const bf16_t* xbin, const bf16_t* yb, const float* g, bf16_t* xb, float* ss_out, float* ss_zero, int gw, int NGW, int lane) {
;     ...
;         RN_LOAD(yn, xn, r0 + 2 * NGW);
; #pragma unroll
;         for (int i = 0; i < 2; ++i) { const int r = r0 + i * NGW; const bool ok = r < M; float y[2][8], x[2][8]; float s2 = 0.f;
; #pragma unroll
;             for (int q = 0; q < 2; ++q) { unpack8(yw[i][q], y[q]); unpack8(xw[i][q], x[q]);
; #pragma unroll
;                 for (int j = 0; j < 8; ++j) s2 += y[q][j] * y[q][j]; }
;             s2 = wave_sum(s2); const float rs = rsqrtf(s2 * (1.0f / 1024.0f) + EPS); float s3 = 0.f;
; #pragma unroll
;             for (int q = 0; q < 2; ++q) { float o[8];
; #pragma unroll
;                 for (int j = 0; j < 4; ++j) { o[j] = x[q][j] + y[q][j] * rs * gv[q][0][j]; o[4 + j] = x[q][4 + j] + y[q][4 + j] * rs * gv[q][1][j]; }
;                 const u32x4 w = pack8(o);
;                 if (ss_out) { float ob[8]; unpack8(w, ob);
; #pragma unroll
;                     for (int j = 0; j < 8; ++j) s3 += ob[j] * ob[j]; }
;                 if (ok) *(u32x4*)(xb + (size_t)r * 1024 + 8 * (lane + 64 * q)) = w; }
;             if (ss_out) s3 = wave_sum(s3);
;             if (lane == 0 && ok) { if (ss_out) ss_out[r] = s3; if (ss_zero) ss_zero[r] = 0.f; } }
.LBB0_61:
	s_waitcnt vmcnt(0)
	v_mov_b64_e32 v[50:51], v[18:19]
	v_mov_b64_e32 v[48:49], v[16:17]
	v_lshlrev_b32_e32 v92, 16, v48
	v_and_b32_e32 v93, 0xffff0000, v48
	v_mov_b64_e32 v[84:85], v[34:35]
	v_lshlrev_b32_e32 v90, 16, v49
	v_and_b32_e32 v91, 0xffff0000, v49
	v_pk_mul_f32 v[48:49], v[92:93], v[92:93]
	v_mov_b64_e32 v[82:83], v[32:33]
	v_pk_mul_f32 v[34:35], v[90:91], v[90:91]
	v_add_f32_e32 v48, v48, v49
	v_lshlrev_b32_e32 v88, 16, v50
	v_and_b32_e32 v89, 0xffff0000, v50
	v_add_f32_e32 v34, v34, v48
	v_pk_mul_f32 v[32:33], v[88:89], v[88:89]
	v_add_f32_e32 v34, v35, v34
	v_mov_b64_e32 v[46:47], v[22:23]
	v_mov_b64_e32 v[74:75], v[30:31]
	v_lshlrev_b32_e32 v86, 16, v51
	v_and_b32_e32 v87, 0xffff0000, v51
	v_add_f32_e32 v32, v32, v34
	v_mov_b64_e32 v[44:45], v[20:21]
	v_mov_b64_e32 v[72:73], v[28:29]
	v_pk_mul_f32 v[30:31], v[86:87], v[86:87]
	v_add_f32_e32 v32, v33, v32
	v_lshlrev_b32_e32 v100, 16, v44
	v_and_b32_e32 v101, 0xffff0000, v44
	v_add_f32_e32 v30, v30, v32
	v_lshlrev_b32_e32 v98, 16, v45
	v_and_b32_e32 v99, 0xffff0000, v45
	v_pk_mul_f32 v[44:45], v[100:101], v[100:101]
	v_add_f32_e32 v30, v31, v30
	v_add_f32_e32 v30, v44, v30
	v_pk_mul_f32 v[52:53], v[98:99], v[98:99]
	v_add_f32_e32 v30, v45, v30
	v_lshlrev_b32_e32 v96, 16, v46
	v_and_b32_e32 v97, 0xffff0000, v46
	v_add_f32_e32 v30, v52, v30
	v_lshlrev_b32_e32 v94, 16, v47
	v_and_b32_e32 v95, 0xffff0000, v47
	v_pk_mul_f32 v[46:47], v[96:97], v[96:97]
	v_add_f32_e32 v30, v53, v30
	v_add_f32_e32 v30, v46, v30
	v_pk_mul_f32 v[50:51], v[94:95], v[94:95]
	v_add_f32_e32 v30, v47, v30
	v_add_f32_e32 v30, v50, v30
	v_add_f32_e32 v44, v51, v30
	s_add_i32 s24, s22, s23
	s_cmp_lt_i32 s24, 0x10100
	s_cselect_b32 s29, s24, s92
	s_cmp_gt_i32 s24, 0x100ff
	s_waitcnt lgkmcnt(0)
	s_nop 1
	v_add_f32_dpp v44, v44, v44 quad_perm:[1,0,3,2] row_mask:0xf bank_mask:0xf
	s_cselect_b32 s24, s92, s24
	s_ashr_i32 s25, s24, 31
	s_lshl_b64 s[24:25], s[24:25], 11
	v_lshl_add_u64 v[20:21], v[66:67], 0, s[24:25]
	s_waitcnt lgkmcnt(0)
	s_nop 1
	v_add_f32_dpp v81, v44, v44 quad_perm:[2,3,0,1] row_mask:0xf bank_mask:0xf
	v_lshl_add_u64 v[28:29], v[68:69], 0, s[24:25]
	s_add_i32 s24, s12, s23
	s_cmp_gt_i32 s24, 0x100ff
	s_cselect_b32 s24, s29, s24
	s_ashr_i32 s25, s24, 31
	s_waitcnt lgkmcnt(0)
	s_nop 1
	v_add_f32_dpp v81, v81, v81 row_half_mirror row_mask:0xf bank_mask:0xf
	s_lshl_b64 s[24:25], s[24:25], 11
	v_lshl_add_u64 v[48:49], v[66:67], 0, s[24:25]
	v_lshl_add_u64 v[56:57], v[68:69], 0, s[24:25]
	global_load_dwordx4 v[16:19], v[20:21], off
	s_nop 0
	global_load_dwordx4 v[20:23], v[20:21], off offset:1024
	s_nop 0
	global_load_dwordx4 v[32:35], v[28:29], off
	s_nop 0
	global_load_dwordx4 v[28:31], v[28:29], off offset:1024
	s_nop 0
	global_load_dwordx4 v[44:47], v[48:49], off
	s_nop 0
	global_load_dwordx4 v[48:51], v[48:49], off offset:1024
	s_nop 0
	global_load_dwordx4 v[52:55], v[56:57], off
	s_nop 0
	global_load_dwordx4 v[56:59], v[56:57], off offset:1024
	s_waitcnt lgkmcnt(0)
	s_nop 1
	v_add_f32_dpp v81, v81, v81 row_mirror row_mask:0xf bank_mask:0xf
	ds_bpermute_b32 v109, v79, v81
	v_lshlrev_b32_e32 v106, 16, v82
	v_and_b32_e32 v107, 0xffff0000, v82
	v_lshlrev_b32_e32 v108, 16, v75
	v_lshlrev_b32_e32 v112, 16, v72
	s_waitcnt lgkmcnt(0)
	v_add_f32_e32 v81, v81, v109
	ds_bpermute_b32 v82, v80, v81
	v_and_b32_e32 v109, 0xffff0000, v75
	v_and_b32_e32 v113, 0xffff0000, v72
	v_lshlrev_b32_e32 v102, 16, v85
	v_and_b32_e32 v103, 0xffff0000, v85
	s_waitcnt lgkmcnt(0)
	v_add_f32_e32 v75, v81, v82
	v_fmamk_f32 v75, v75, 0x3a800000, v134
	v_mul_f32_e32 v81, 0x4b800000, v75
	v_cmp_gt_f32_e32 vcc, s13, v75
	v_lshlrev_b32_e32 v104, 16, v84
	v_and_b32_e32 v105, 0xffff0000, v84
	v_cndmask_b32_e32 v75, v75, v81, vcc
	v_rsq_f32_e32 v81, v75
	v_lshlrev_b32_e32 v84, 16, v83
	v_and_b32_e32 v85, 0xffff0000, v83
	v_lshlrev_b32_e32 v110, 16, v74
	v_mul_f32_e32 v72, 0x45800000, v81
	v_cndmask_b32_e32 v72, v81, v72, vcc
	v_pk_mul_f32 v[82:83], v[72:73], v[92:93] op_sel_hi:[0,1]
	v_pk_fma_f32 v[82:83], v[8:9], v[82:83], v[106:107]
	v_pk_mul_f32 v[90:91], v[72:73], v[90:91] op_sel_hi:[0,1]
	v_cvt_pk_bf16_f32 v82, v82, v83
	v_pk_fma_f32 v[84:85], v[10:11], v[90:91], v[84:85]
	v_pk_mul_f32 v[86:87], v[72:73], v[86:87] op_sel_hi:[0,1]
	v_and_b32_e32 v81, 0xffff0000, v82
	v_and_b32_e32 v111, 0xffff0000, v74
	v_lshlrev_b32_e32 v74, 16, v73
	v_and_b32_e32 v75, 0xffff0000, v73
	v_pk_mul_f32 v[88:89], v[72:73], v[88:89] op_sel_hi:[0,1]
	v_pk_fma_f32 v[86:87], v[14:15], v[86:87], v[102:103]
	v_cvt_pk_bf16_f32 v83, v84, v85
	v_lshlrev_b32_e32 v73, 16, v82
	v_mul_f32_e32 v81, v81, v81
	v_pk_fma_f32 v[88:89], v[12:13], v[88:89], v[104:105]
	v_cvt_pk_bf16_f32 v85, v86, v87
	v_lshlrev_b32_e32 v86, 16, v83
	v_fmac_f32_e32 v81, v73, v73
	v_cvt_pk_bf16_f32 v84, v88, v89
	v_and_b32_e32 v87, 0xffff0000, v83
	v_fmac_f32_e32 v81, v86, v86
	v_lshlrev_b32_e32 v88, 16, v84
	v_fmac_f32_e32 v81, v87, v87
	v_and_b32_e32 v89, 0xffff0000, v84
	v_fmac_f32_e32 v81, v88, v88
	v_lshlrev_b32_e32 v90, 16, v85
	v_fmac_f32_e32 v81, v89, v89
	v_and_b32_e32 v91, 0xffff0000, v85
	v_fmac_f32_e32 v81, v90, v90
	v_pk_mul_f32 v[86:87], v[72:73], v[100:101] op_sel_hi:[0,1]
	v_fmac_f32_e32 v81, v91, v91
	v_pk_fma_f32 v[86:87], v[0:1], v[86:87], v[112:113]
	v_pk_mul_f32 v[88:89], v[72:73], v[96:97] op_sel_hi:[0,1]
	v_pk_mul_f32 v[90:91], v[72:73], v[98:99] op_sel_hi:[0,1]
	v_pk_mul_f32 v[72:73], v[72:73], v[94:95] op_sel_hi:[0,1]
	v_pk_fma_f32 v[88:89], v[4:5], v[88:89], v[110:111]
	v_pk_fma_f32 v[72:73], v[6:7], v[72:73], v[108:109]
	v_cvt_pk_bf16_f32 v86, v86, v87
	v_pk_fma_f32 v[74:75], v[2:3], v[90:91], v[74:75]
	v_cvt_pk_bf16_f32 v88, v88, v89
	v_cvt_pk_bf16_f32 v89, v72, v73
	v_lshlrev_b32_e32 v72, 16, v86
	v_cvt_pk_bf16_f32 v87, v74, v75
	v_and_b32_e32 v73, 0xffff0000, v86
	v_fmac_f32_e32 v81, v72, v72
	v_lshlrev_b32_e32 v74, 16, v87
	v_fmac_f32_e32 v81, v73, v73
	v_and_b32_e32 v75, 0xffff0000, v87
	v_fmac_f32_e32 v81, v74, v74
	v_lshlrev_b32_e32 v90, 16, v88
	v_fmac_f32_e32 v81, v75, v75
	v_and_b32_e32 v91, 0xffff0000, v88
	v_fmac_f32_e32 v81, v90, v90
	v_lshlrev_b32_e32 v92, 16, v89
	v_fmac_f32_e32 v81, v91, v91
	v_and_b32_e32 v93, 0xffff0000, v89
	v_fmac_f32_e32 v81, v92, v92
	v_fmac_f32_e32 v81, v93, v93
	v_lshl_add_u64 v[74:75], s[54:55], 0, v[70:71]
	s_mov_b32 s24, 0x3b40000
	v_add_co_u32_e32 v74, vcc, s24, v74
	s_waitcnt lgkmcnt(0)
	s_nop 1
	v_add_f32_dpp v72, v81, v81 quad_perm:[1,0,3,2] row_mask:0xf bank_mask:0xf
	v_addc_co_u32_e32 v75, vcc, 0, v75, vcc
	global_store_dwordx4 v[74:75], v[82:85], off
	global_store_dwordx4 v[74:75], v[86:89], off offset:1024
	s_waitcnt lgkmcnt(0)
	s_nop 1
	v_add_f32_dpp v72, v72, v72 quad_perm:[2,3,0,1] row_mask:0xf bank_mask:0xf
	s_waitcnt lgkmcnt(0)
	s_nop 1
	v_add_f32_dpp v72, v72, v72 row_half_mirror row_mask:0xf bank_mask:0xf
	s_waitcnt lgkmcnt(0)
	s_nop 1
	v_add_f32_dpp v72, v72, v72 row_mirror row_mask:0xf bank_mask:0xf
	ds_bpermute_b32 v73, v79, v72
	s_waitcnt lgkmcnt(0)
	v_add_f32_e32 v72, v72, v73
	ds_bpermute_b32 v73, v80, v72
	s_and_saveexec_b64 s[48:49], s[40:41]
	s_cbranch_execz .LBB0_63
; __device__ __forceinline__ void unpack8(const u32x4 w, float (&f)[8]) { f[0] = bflo(w.x); f[1] = bfhi(w.x); f[2] = bflo(w.y); f[3] = bfhi(w.y); f[4] = bflo(w.z); f[5] = bfhi(w.z); f[6] = bflo(w.w); f[7] = bfhi(w.w); }
; __device__ __forceinline__ u32x4 pack8(const float (&f)[8]) { u32x4 w; w.x = pkbf(f[0], f[1]); w.y = pkbf(f[2], f[3]); w.z = pkbf(f[4], f[5]); w.w = pkbf(f[6], f[7]); return w; }
; __device__ __forceinline__ void resnorm_pass(const float* xa, const float* xs, const bf16_t* xbin, const bf16_t* yb, const float* g, bf16_t* xb, float* ss_out, float* ss_zero, int gw, int NGW, int lane) {
;     ...
;         for (int i = 0; i < 2; ++i) { const int r = r0 + i * NGW; const bool ok = r < M; float y[2][8], x[2][8]; float s2 = 0.f;
; #pragma unroll
;             for (int q = 0; q < 2; ++q) { unpack8(yw[i][q], y[q]); unpack8(xw[i][q], x[q]);
; #pragma unroll
;                 for (int j = 0; j < 8; ++j) s2 += y[q][j] * y[q][j]; }
;             s2 = wave_sum(s2); const float rs = rsqrtf(s2 * (1.0f / 1024.0f) + EPS); float s3 = 0.f;
; #pragma unroll
;             for (int q = 0; q < 2; ++q) { float o[8];
; #pragma unroll
;                 for (int j = 0; j < 4; ++j) { o[j] = x[q][j] + y[q][j] * rs * gv[q][0][j]; o[4 + j] = x[q][4 + j] + y[q][4 + j] * rs * gv[q][1][j]; }
;                 const u32x4 w = pack8(o);
;                 if (ss_out) { float ob[8]; unpack8(w, ob);
; #pragma unroll
;                     for (int j = 0; j < 8; ++j) s3 += ob[j] * ob[j]; }
;                 if (ok) *(u32x4*)(xb + (size_t)r * 1024 + 8 * (lane + 64 * q)) = w; }
;             if (ss_out) s3 = wave_sum(s3);
;             if (lane == 0 && ok) { if (ss_out) ss_out[r] = s3; if (ss_zero) ss_zero[r] = 0.f; } }
	s_add_u32 s24, s54, s20
	s_addc_u32 s25, s55, s21
	s_waitcnt lgkmcnt(0)
	v_add_f32_e32 v72, v72, v73
	v_mov_b32_e32 v73, 0x280000
	global_store_dword v73, v72, s[24:25]
	v_mov_b32_e32 v72, 0x190000
	global_store_dword v72, v133, s[24:25]
.LBB0_63:
	s_or_b64 exec, exec, s[48:49]
	v_lshlrev_b32_e32 v100, 16, v40
	v_and_b32_e32 v101, 0xffff0000, v40
	v_lshlrev_b32_e32 v96, 16, v41
	v_and_b32_e32 v97, 0xffff0000, v41
	v_pk_mul_f32 v[40:41], v[100:101], v[100:101]
	v_pk_mul_f32 v[98:99], v[96:97], v[96:97]
	v_add_f32_e32 v40, v40, v41
	v_lshlrev_b32_e32 v94, 16, v42
	v_and_b32_e32 v95, 0xffff0000, v42
	v_add_f32_e32 v40, v98, v40
	v_lshlrev_b32_e32 v90, 16, v43
	v_and_b32_e32 v91, 0xffff0000, v43
	v_pk_mul_f32 v[42:43], v[94:95], v[94:95]
	v_add_f32_e32 v40, v99, v40
	v_add_f32_e32 v40, v42, v40
	v_pk_mul_f32 v[92:93], v[90:91], v[90:91]
	v_add_f32_e32 v40, v43, v40
	v_lshlrev_b32_e32 v72, 16, v60
	s_waitcnt lgkmcnt(0)
	v_and_b32_e32 v73, 0xffff0000, v60
	v_add_f32_e32 v40, v92, v40
	v_pk_mul_f32 v[82:83], v[72:73], v[72:73]
	v_add_f32_e32 v40, v93, v40
	v_lshlrev_b32_e32 v60, 16, v61
	v_and_b32_e32 v61, 0xffff0000, v61
	v_add_f32_e32 v40, v82, v40
	v_pk_mul_f32 v[84:85], v[60:61], v[60:61]
	v_add_f32_e32 v40, v83, v40
	v_lshlrev_b32_e32 v74, 16, v62
	v_and_b32_e32 v75, 0xffff0000, v62
	v_add_f32_e32 v40, v84, v40
	v_pk_mul_f32 v[86:87], v[74:75], v[74:75]
	v_add_f32_e32 v40, v85, v40
	v_lshlrev_b32_e32 v62, 16, v63
	v_and_b32_e32 v63, 0xffff0000, v63
	v_add_f32_e32 v40, v86, v40
	v_pk_mul_f32 v[88:89], v[62:63], v[62:63]
	v_add_f32_e32 v40, v87, v40
	v_add_f32_e32 v40, v88, v40
	v_add_f32_e32 v40, v89, v40
	v_lshlrev_b32_e32 v42, 16, v39
	v_and_b32_e32 v43, 0xffff0000, v39
	v_lshlrev_b32_e32 v84, 16, v36
	v_and_b32_e32 v85, 0xffff0000, v36
	s_waitcnt lgkmcnt(0)
	s_nop 1
	v_add_f32_dpp v40, v40, v40 quad_perm:[1,0,3,2] row_mask:0xf bank_mask:0xf
	s_add_i32 s48, s3, s23
	s_cmp_lt_i32 s48, 0x10100
	v_lshlrev_b32_e32 v82, 16, v38
	v_and_b32_e32 v83, 0xffff0000, v38
	s_waitcnt lgkmcnt(0)
	s_nop 1
	v_add_f32_dpp v40, v40, v40 quad_perm:[2,3,0,1] row_mask:0xf bank_mask:0xf
	v_lshlrev_b32_e32 v38, 16, v37
	s_cselect_b64 s[56:57], -1, 0
	s_ashr_i32 s49, s48, 31
	s_lshl_b64 s[24:25], s[48:49], 11
	s_waitcnt lgkmcnt(0)
	s_nop 1
	v_add_f32_dpp v40, v40, v40 row_half_mirror row_mask:0xf bank_mask:0xf
	s_add_u32 s58, s26, s24
	s_addc_u32 s59, s27, s25
	s_cmp_gt_i32 s48, 0x100ff
	s_waitcnt lgkmcnt(0)
	s_nop 1
	v_add_f32_dpp v40, v40, v40 row_mirror row_mask:0xf bank_mask:0xf
	ds_bpermute_b32 v41, v79, v40
	s_waitcnt lgkmcnt(0)
	v_add_f32_e32 v40, v40, v41
	ds_bpermute_b32 v41, v80, v40
	s_waitcnt lgkmcnt(0)
	v_add_f32_e32 v39, v40, v41
	v_fmamk_f32 v39, v39, 0x3a800000, v134
	v_mul_f32_e32 v40, 0x4b800000, v39
	v_cmp_gt_f32_e32 vcc, s13, v39
	s_nop 1
	v_cndmask_b32_e32 v39, v39, v40, vcc
	v_rsq_f32_e32 v40, v39
	v_and_b32_e32 v39, 0xffff0000, v37
	v_mul_f32_e32 v36, 0x45800000, v40
	v_cndmask_b32_e32 v40, v40, v36, vcc
	v_pk_mul_f32 v[36:37], v[40:41], v[100:101] op_sel_hi:[0,1]
	v_pk_fma_f32 v[36:37], v[8:9], v[36:37], v[84:85]
	v_pk_mul_f32 v[84:85], v[40:41], v[94:95] op_sel_hi:[0,1]
	v_pk_fma_f32 v[82:83], v[12:13], v[84:85], v[82:83]
	v_pk_mul_f32 v[84:85], v[40:41], v[96:97] op_sel_hi:[0,1]
	v_pk_fma_f32 v[38:39], v[10:11], v[84:85], v[38:39]
	v_pk_mul_f32 v[84:85], v[40:41], v[90:91] op_sel_hi:[0,1]
	v_pk_fma_f32 v[42:43], v[14:15], v[84:85], v[42:43]
	v_cvt_pk_bf16_f32 v36, v36, v37
	v_cvt_pk_bf16_f32 v37, v38, v39
	v_cvt_pk_bf16_f32 v38, v82, v83
	v_cvt_pk_bf16_f32 v39, v42, v43
	v_lshlrev_b32_e32 v42, 1, v64
	s_cbranch_scc1 .LBB0_65
	global_store_dwordx4 v42, v[36:39], s[58:59]

; __device__ __forceinline__ void unpack8(const u32x4 w, float (&f)[8]) { f[0] = bflo(w.x); f[1] = bfhi(w.x); f[2] = bflo(w.y); f[3] = bfhi(w.y); f[4] = bflo(w.z); f[5] = bfhi(w.z); f[6] = bflo(w.w); f[7] = bfhi(w.w); }
; __device__ __forceinline__ void resnorm_pass(const float* xa, const float* xs, const bf16_t* xbin, const bf16_t* yb, const float* g, bf16_t* xb, float* ss_out, float* ss_zero, int gw, int NGW, int lane) {
;     ...
;                 if (ss_out) { float ob[8]; unpack8(w, ob);
; #pragma unroll
;                     for (int j = 0; j < 8; ++j) s3 += ob[j] * ob[j]; }
;                 if (ok) *(u32x4*)(xb + (size_t)r * 1024 + 8 * (lane + 64 * q)) = w; }
;             if (ss_out) s3 = wave_sum(s3);
;             if (lane == 0 && ok) { if (ss_out) ss_out[r] = s3; if (ss_zero) ss_zero[r] = 0.f; } }
.LBB0_67:
	v_lshlrev_b32_e32 v40, 16, v36
	v_and_b32_e32 v36, 0xffff0000, v36
	v_mul_f32_e32 v36, v36, v36
	v_lshlrev_b32_e32 v41, 16, v37
	v_fmac_f32_e32 v36, v40, v40
	v_and_b32_e32 v37, 0xffff0000, v37
	v_fmac_f32_e32 v36, v41, v41
	v_lshlrev_b32_e32 v42, 16, v38
	v_fmac_f32_e32 v36, v37, v37
	v_and_b32_e32 v38, 0xffff0000, v38
	v_fmac_f32_e32 v36, v42, v42
	v_lshlrev_b32_e32 v43, 16, v39
	v_fmac_f32_e32 v36, v38, v38
	v_and_b32_e32 v39, 0xffff0000, v39
	v_fmac_f32_e32 v36, v43, v43
	v_fmac_f32_e32 v36, v39, v39
	v_lshlrev_b32_e32 v37, 16, v24
	v_and_b32_e32 v24, 0xffff0000, v24
	v_fmac_f32_e32 v36, v37, v37
	v_lshlrev_b32_e32 v38, 16, v25
	v_fmac_f32_e32 v36, v24, v24
	v_and_b32_e32 v25, 0xffff0000, v25
	v_fmac_f32_e32 v36, v38, v38
	v_lshlrev_b32_e32 v39, 16, v26
	v_fmac_f32_e32 v36, v25, v25
	v_and_b32_e32 v26, 0xffff0000, v26
	v_fmac_f32_e32 v36, v39, v39
	v_lshlrev_b32_e32 v40, 16, v27
	v_fmac_f32_e32 v36, v26, v26
	v_and_b32_e32 v27, 0xffff0000, v27
	v_fmac_f32_e32 v36, v40, v40
	v_fmac_f32_e32 v36, v27, v27
	s_and_b64 s[24:25], s[40:41], s[56:57]
	s_waitcnt lgkmcnt(0)
	s_nop 1
	v_add_f32_dpp v24, v36, v36 quad_perm:[1,0,3,2] row_mask:0xf bank_mask:0xf
	s_waitcnt lgkmcnt(0)
	s_nop 1
	v_add_f32_dpp v24, v24, v24 quad_perm:[2,3,0,1] row_mask:0xf bank_mask:0xf
	s_waitcnt lgkmcnt(0)
	s_nop 1
	v_add_f32_dpp v24, v24, v24 row_half_mirror row_mask:0xf bank_mask:0xf
	s_waitcnt lgkmcnt(0)
	s_nop 1
	v_add_f32_dpp v24, v24, v24 row_mirror row_mask:0xf bank_mask:0xf
	ds_bpermute_b32 v25, v79, v24
	s_waitcnt lgkmcnt(0)
	v_add_f32_e32 v24, v24, v25
	ds_bpermute_b32 v25, v80, v24
	s_and_saveexec_b64 s[56:57], s[24:25]
	s_cbranch_execz .LBB0_60
	s_lshl_b64 s[24:25], s[48:49], 2
	s_add_u32 s48, s0, s24
	s_addc_u32 s49, s1, s25
	s_add_u32 s24, s8, s24
	s_addc_u32 s25, s9, s25
	s_waitcnt lgkmcnt(0)
	v_add_f32_e32 v24, v24, v25
	global_store_dword v133, v24, s[24:25]
	global_store_dword v133, v133, s[48:49]
	s_branch .LBB0_60

; __device__ __forceinline__ float bflo(unsigned w) { return __uint_as_float(w << 16); }
; __device__ __forceinline__ float bfhi(unsigned w) { return __uint_as_float(w & 0xffff0000u); }
; __device__ __forceinline__ u32x4 pack8(const float (&f)[8]) { u32x4 w; w.x = pkbf(f[0], f[1]); w.y = pkbf(f[2], f[3]); w.z = pkbf(f[4], f[5]); w.w = pkbf(f[6], f[7]); return w; }
; __device__ __forceinline__ void e1_pass(ArgP ap, int l, int gw, int NGW, int lane) {
;     ...
;         float co[8]; float ss = 0.f;
; #pragma unroll
;         for (int j = 0; j < 8; ++j) { const float cv = u0[j] * wconv[c8 + j] + u1[j] * wconv[512 + c8 + j] + u2[j] * wconv[1024 + c8 + j]; co[j] = gb[j] * cv; ss += co[j] * co[j]; }
;         ss = wave_sum(ss); { const float rs = rsqrtf(ss * (1.0f / 512.0f) + EPS);
; #pragma unroll
;             for (int j = 0; j < 8; ++j) co[j] *= rs; }
;         *(u32x4*)(A3 + (size_t)r * 1024 + c8) = pack8(co);
;         if (t >= L - 2) { float* d = out + (isp ? O_CVP + ((size_t)(l * 32 + b) * 2 + (t - (L - 2))) * 512 : O_CVS + ((size_t)(l * 8 + b) * 2 + (t - (L - 2))) * 512) + c8;
;             *(f32x4*)d = (f32x4){u2[0], u2[1], u2[2], u2[3]}; *(f32x4*)(d + 4) = (f32x4){u2[4], u2[5], u2[6], u2[7]}; }
;         { const u32x2 w = w_kv; float v[4] = {bflo(w.x), bfhi(w.x), bflo(w.y), bfhi(w.y)};
;             float s2 = (v[0] * v[0] + v[1] * v[1]) + (v[2] * v[2] + v[3] * v[3]); s2 = wave_sum(s2); const float rs = rsqrtf(s2 * (1.0f / 256.0f) + EPS);
.LBB0_495:
	s_waitcnt vmcnt(14)
	v_lshlrev_b32_e32 v12, 16, v40
	v_and_b32_e32 v13, 0xffff0000, v40
	v_lshlrev_b32_e32 v14, 16, v41
	v_and_b32_e32 v15, 0xffff0000, v41
	v_lshlrev_b32_e32 v8, 16, v42
	v_and_b32_e32 v9, 0xffff0000, v42
	v_lshlrev_b32_e32 v10, 16, v43
	v_and_b32_e32 v11, 0xffff0000, v43
	s_waitcnt vmcnt(17)
	v_lshlrev_b32_e32 v96, 16, v44
	v_and_b32_e32 v97, 0xffff0000, v44
	v_lshlrev_b32_e32 v44, 16, v45
	v_and_b32_e32 v45, 0xffff0000, v45
	v_lshlrev_b32_e32 v126, 16, v46
	v_and_b32_e32 v127, 0xffff0000, v46
	v_lshlrev_b32_e32 v46, 16, v47
	v_and_b32_e32 v47, 0xffff0000, v47
	s_ashr_i32 s56, s29, 11
	s_and_b64 s[24:25], s[44:45], exec
	s_cselect_b32 s42, 0x7fe, 30
	s_cmp_lt_u32 s10, s42
	v_pk_mul_f32 v[6:7], v[6:7], v[214:215]
	s_nop 0
	v_pk_fma_f32 v[6:7], v[98:99], v[206:207], v[6:7]
	v_pk_mul_f32 v[0:1], v[0:1], v[208:209]
	v_pk_mul_f32 v[2:3], v[2:3], v[210:211]
	v_pk_fma_f32 v[0:1], v[90:91], v[200:201], v[0:1]
	v_pk_fma_f32 v[2:3], v[92:93], v[202:203], v[2:3]
	v_pk_mul_f32 v[4:5], v[4:5], v[212:213]
	v_pk_fma_f32 v[6:7], v[222:223], v[10:11], v[6:7]
	v_pk_fma_f32 v[0:1], v[216:217], v[12:13], v[0:1]
	v_pk_fma_f32 v[2:3], v[218:219], v[14:15], v[2:3]
	v_pk_mul_f32 v[0:1], v[0:1], v[96:97]
	v_pk_fma_f32 v[4:5], v[94:95], v[204:205], v[4:5]
	v_pk_mul_f32 v[2:3], v[2:3], v[44:45]
	v_pk_mul_f32 v[40:41], v[0:1], v[0:1]
	v_pk_fma_f32 v[4:5], v[220:221], v[8:9], v[4:5]
	v_pk_mul_f32 v[42:43], v[2:3], v[2:3]
	v_add_f32_e32 v40, v40, v41
	v_pk_mul_f32 v[4:5], v[4:5], v[126:127]
	v_add_f32_e32 v40, v40, v42
	v_pk_mul_f32 v[94:95], v[4:5], v[4:5]
	v_add_f32_e32 v40, v40, v43
	v_pk_mul_f32 v[6:7], v[6:7], v[46:47]
	v_add_f32_e32 v40, v40, v94
	v_pk_mul_f32 v[46:47], v[6:7], v[6:7]
	v_add_f32_e32 v40, v40, v95
	v_add_f32_e32 v40, v40, v46
	v_add_f32_e32 v40, v40, v47
	s_waitcnt lgkmcnt(0)
	s_nop 1
	v_add_f32_dpp v40, v40, v40 quad_perm:[1,0,3,2] row_mask:0xf bank_mask:0xf
	s_waitcnt lgkmcnt(0)
	s_nop 1
	v_add_f32_dpp v40, v40, v40 quad_perm:[2,3,0,1] row_mask:0xf bank_mask:0xf
	s_waitcnt lgkmcnt(0)
	s_nop 1
	v_add_f32_dpp v40, v40, v40 row_half_mirror row_mask:0xf bank_mask:0xf
	s_waitcnt lgkmcnt(0)
	s_nop 1
	v_add_f32_dpp v40, v40, v40 row_mirror row_mask:0xf bank_mask:0xf
	ds_bpermute_b32 v41, v105, v40
	s_waitcnt lgkmcnt(0)
	v_add_f32_e32 v40, v40, v41
	ds_bpermute_b32 v41, v106, v40
	s_waitcnt lgkmcnt(0)
	v_add_f32_e32 v40, v40, v41
	v_fmamk_f32 v40, v40, 0x3b000000, v134
	v_cmp_gt_f32_e32 vcc, s13, v40
	v_mul_f32_e32 v41, 0x4b800000, v40
	s_nop 0
	v_cndmask_b32_e32 v40, v40, v41, vcc
	v_rsq_f32_e32 v40, v40
	s_nop 0
	v_mul_f32_e32 v41, 0x45800000, v40
	v_cndmask_b32_e32 v40, v40, v41, vcc
	v_pk_mul_f32 v[0:1], v[0:1], v[40:41] op_sel_hi:[1,0]
	v_pk_mul_f32 v[2:3], v[2:3], v[40:41] op_sel_hi:[1,0]
	v_pk_mul_f32 v[4:5], v[4:5], v[40:41] op_sel_hi:[1,0]
	v_pk_mul_f32 v[6:7], v[6:7], v[40:41] op_sel_hi:[1,0]
	v_cvt_pk_bf16_f32 v0, v0, v1
	v_cvt_pk_bf16_f32 v1, v2, v3
	v_cvt_pk_bf16_f32 v2, v4, v5
	v_cvt_pk_bf16_f32 v3, v6, v7
	global_store_dwordx4 v[82:83], v[0:3], off
	s_cbranch_scc1 .LBB0_497
	s_add_i32 s10, s51, s0
	s_sub_i32 s42, s33, 30
	s_add_i32 s43, s56, s22
	s_add_i32 s46, s50, 0xfffff802
	s_and_b64 s[24:25], s[44:45], exec
	s_cselect_b32 s24, s46, s42
	s_cselect_b32 s42, s43, s10
	s_mov_b32 s10, 0x19100000
	s_cselect_b32 s10, s10, 0x191d0000
	s_ashr_i32 s25, s24, 31
	s_lshl_b64 s[24:25], s[24:25], 11
	s_ashr_i32 s43, s42, 31
	v_lshl_add_u64 v[0:1], v[62:63], 0, s[24:25]
	v_lshl_add_u64 v[0:1], v[0:1], 0, s[10:11]
	s_lshl_b64 s[24:25], s[42:43], 12
	v_lshl_add_u64 v[0:1], v[0:1], 0, s[24:25]
	global_store_dwordx4 v[0:1], v[12:15], off
	global_store_dwordx4 v[0:1], v[8:11], off offset:16
.LBB0_497:
	s_nop 1
	v_and_b32_e32 v11, 0xffff0000, v84
	v_lshlrev_b32_e32 v4, 16, v85
	v_and_b32_e32 v9, 0xffff0000, v85
	v_mov_b32_e32 v8, v11
	v_lshlrev_b32_e32 v6, 16, v84
	v_mov_b32_e32 v7, v4
	v_pk_mul_f32 v[12:13], v[8:9], v[8:9]
	s_mov_b64 s[42:43], -1
	v_pk_fma_f32 v[12:13], v[6:7], v[6:7], v[12:13]
	s_and_b64 vcc, exec, s[38:39]
	v_add_f32_e32 v5, v12, v13
	s_waitcnt lgkmcnt(0)
	s_nop 1
	v_add_f32_dpp v5, v5, v5 quad_perm:[1,0,3,2] row_mask:0xf bank_mask:0xf
	s_waitcnt lgkmcnt(0)
	s_nop 1
	v_add_f32_dpp v5, v5, v5 quad_perm:[2,3,0,1] row_mask:0xf bank_mask:0xf
	s_waitcnt lgkmcnt(0)
	s_nop 1
	v_add_f32_dpp v5, v5, v5 row_half_mirror row_mask:0xf bank_mask:0xf
	s_waitcnt lgkmcnt(0)
	s_nop 1
	v_add_f32_dpp v5, v5, v5 row_mirror row_mask:0xf bank_mask:0xf
	ds_bpermute_b32 v7, v105, v5
	s_waitcnt lgkmcnt(0)
	v_add_f32_e32 v5, v5, v7
	ds_bpermute_b32 v7, v106, v5
	s_cbranch_vccz .LBB0_499
	s_add_i32 s24, s51, s0
	s_ashr_i32 s25, s24, 31
	s_lshl_b32 s10, s33, 8
	s_lshl_b64 s[46:47], s[24:25], 13
	s_or_b32 s10, s10, 0x6450000
	s_mov_b64 s[42:43], 0

; __device__ __forceinline__ unsigned pkbf(float lo, float hi) { f2_t v = {lo, hi}; return __builtin_bit_cast(unsigned, __builtin_convertvector(v, bf2_t)); }
; __device__ __forceinline__ void prologue(ArgP ap, LAS unsigned char* lds, int gw, int NGW, int wave, int lane) {
;     ...
;     PX_LOAD(v, gw);
;     for (int r0 = gw; r0 < M; r0 += 2 * NGW) {
;         PX_LOAD(vn, r0 + 2 * NGW);
; #pragma unroll
;         for (int i = 0; i < 2; ++i) { const int r = r0 + i * NGW; const bool ok = r < M; float ss = 0.f;
; #pragma unroll
;             for (int q = 0; q < 2; ++q) { const int c8 = 8 * (lane + 64 * q); const f32x4 v0 = v[i][q][0], v1 = v[i][q][1];
;                 ss += (v0[0] * v0[0] + v0[1] * v0[1]) + (v0[2] * v0[2] + v0[3] * v0[3]) + (v1[0] * v1[0] + v1[1] * v1[1]) + (v1[2] * v1[2] + v1[3] * v1[3]);
;                 u32x4 w; w.x = pkbf(v0[0], v0[1]); w.y = pkbf(v0[2], v0[3]); w.z = pkbf(v1[0], v1[1]); w.w = pkbf(v1[2], v1[3]); if (ok) *(u32x4*)(xb0 + (size_t)r * 1024 + c8) = w; }
;             ss = wave_sum(ss); if (lane == 0 && ok) { ssA[r] = ss; ((float*)(ws + WS_SSQ))[r] = 0.f; } }
.LBB0_979:
	s_add_i32 s2, s20, s81
	s_add_i32 s3, s12, s81
	s_cmp_gt_i32 s3, 0x100ff
	s_cselect_b32 s3, s92, s3
	s_add_i32 s4, s3, 0xffff0000
	s_ashr_i32 s5, s3, 31
	s_cmp_lt_i32 s3, 0x10000
	s_cselect_b32 s4, s3, s4
	s_cselect_b32 s3, 0, 8
	s_cselect_b32 s5, s5, 0
	s_add_u32 s6, s70, s3
	s_addc_u32 s7, s71, 0
	s_load_dwordx2 s[6:7], s[6:7], 0x0
	s_lshl_b64 s[4:5], s[4:5], 12
	v_lshlrev_b32_e32 v40, 2, v64
	s_waitcnt vmcnt(0)
	v_mul_f32_e32 v73, v61, v61
	v_mul_f32_e32 v74, v63, v63
	s_waitcnt lgkmcnt(0)
	s_add_u32 s4, s6, s4
	s_addc_u32 s5, s7, s5
	s_add_i32 s3, s9, s81
	s_cmp_gt_i32 s3, 0x100ff
	s_cselect_b32 s3, s92, s3
	s_ashr_i32 s6, s3, 31
	s_add_i32 s16, s3, 0xffff0000
	s_cmp_lt_i32 s3, 0x10000
	s_cselect_b32 s7, s6, 0
	s_cselect_b32 s6, s3, s16
	s_cselect_b32 s3, 0, 8
	s_add_u32 s16, s70, s3
	s_addc_u32 s17, s71, 0
	s_load_dwordx2 s[16:17], s[16:17], 0x0
	global_load_dwordx4 v[20:23], v40, s[4:5] offset:16
	global_load_dwordx4 v[28:31], v40, s[4:5]
	global_load_dwordx4 v[16:19], v40, s[4:5] offset:2064
	global_load_dwordx4 v[24:27], v40, s[4:5] offset:2048
	s_lshl_b64 s[4:5], s[6:7], 12
	v_fmac_f32_e32 v73, v60, v60
	v_fmac_f32_e32 v74, v62, v62
	s_waitcnt lgkmcnt(0)
	s_add_u32 s4, s16, s4
	s_addc_u32 s5, s17, s5
	global_load_dwordx4 v[36:39], v40, s[4:5] offset:16
	global_load_dwordx4 v[44:47], v40, s[4:5]
	global_load_dwordx4 v[32:35], v40, s[4:5] offset:2064
	s_nop 0
	global_load_dwordx4 v[40:43], v40, s[4:5] offset:2048
	v_add_f32_e32 v73, v73, v74
	v_mul_f32_e32 v74, v57, v57
	v_fmac_f32_e32 v74, v56, v56
	v_add_f32_e32 v73, v73, v74
	v_mul_f32_e32 v74, v59, v59
	v_fmac_f32_e32 v74, v58, v58
	v_add_f32_e32 v73, v74, v73
	v_mul_f32_e32 v74, v53, v53
	v_mul_f32_e32 v75, v55, v55
	v_fmac_f32_e32 v74, v52, v52
	v_fmac_f32_e32 v75, v54, v54
	v_add_f32_e32 v74, v74, v75
	v_mul_f32_e32 v75, v49, v49
	v_fmac_f32_e32 v75, v48, v48
	v_add_f32_e32 v74, v74, v75
	v_mul_f32_e32 v75, v51, v51
	v_fmac_f32_e32 v75, v50, v50
	v_add_f32_e32 v74, v75, v74
	v_add_f32_e32 v73, v73, v74
	v_cvt_pk_bf16_f32 v60, v60, v61
	v_cvt_pk_bf16_f32 v61, v62, v63
	v_cvt_pk_bf16_f32 v62, v56, v57
	v_cvt_pk_bf16_f32 v56, v52, v53
	s_waitcnt lgkmcnt(0)
	s_nop 1
	v_add_f32_dpp v73, v73, v73 quad_perm:[1,0,3,2] row_mask:0xf bank_mask:0xf
	s_ashr_i32 s3, s2, 31
	s_lshl_b64 s[4:5], s[2:3], 11
	v_cvt_pk_bf16_f32 v63, v58, v59
	v_cvt_pk_bf16_f32 v57, v54, v55
	s_waitcnt lgkmcnt(0)
	s_nop 1
	v_add_f32_dpp v73, v73, v73 quad_perm:[2,3,0,1] row_mask:0xf bank_mask:0xf
	v_cvt_pk_bf16_f32 v58, v48, v49
	v_cvt_pk_bf16_f32 v59, v50, v51
	s_waitcnt lgkmcnt(0)
	s_nop 1
	v_add_f32_dpp v73, v73, v73 row_half_mirror row_mask:0xf bank_mask:0xf
	v_lshl_add_u64 v[74:75], v[66:67], 0, s[4:5]
	global_store_dwordx4 v[74:75], v[60:63], off
	global_store_dwordx4 v[74:75], v[56:59], off offset:1024
	s_waitcnt lgkmcnt(0)
	s_nop 1
	v_add_f32_dpp v73, v73, v73 row_mirror row_mask:0xf bank_mask:0xf
	ds_bpermute_b32 v76, v71, v73
	s_waitcnt lgkmcnt(0)
	v_add_f32_e32 v52, v73, v76
	ds_bpermute_b32 v53, v72, v52
	s_and_saveexec_b64 s[4:5], s[40:41]
	s_cbranch_execz .LBB0_981
	s_lshl_b64 s[2:3], s[2:3], 2
	s_add_u32 s6, s18, s2
	s_addc_u32 s7, s19, s3
	s_waitcnt lgkmcnt(0)
	v_add_f32_e32 v48, v52, v53
	s_add_u32 s2, s0, s2
	s_addc_u32 s3, s1, s3
	global_store_dword v133, v48, s[6:7]
	global_store_dword v133, v133, s[2:3]

; __device__ __forceinline__ unsigned pkbf(float lo, float hi) { f2_t v = {lo, hi}; return __builtin_bit_cast(unsigned, __builtin_convertvector(v, bf2_t)); }
; __device__ __forceinline__ void prologue(ArgP ap, LAS unsigned char* lds, int gw, int NGW, int wave, int lane) {
;     ...
;         for (int i = 0; i < 2; ++i) { const int r = r0 + i * NGW; const bool ok = r < M; float ss = 0.f;
; #pragma unroll
;             for (int q = 0; q < 2; ++q) { const int c8 = 8 * (lane + 64 * q); const f32x4 v0 = v[i][q][0], v1 = v[i][q][1];
;                 ss += (v0[0] * v0[0] + v0[1] * v0[1]) + (v0[2] * v0[2] + v0[3] * v0[3]) + (v1[0] * v1[0] + v1[1] * v1[1]) + (v1[2] * v1[2] + v1[3] * v1[3]);
;                 u32x4 w; w.x = pkbf(v0[0], v0[1]); w.y = pkbf(v0[2], v0[3]); w.z = pkbf(v1[0], v1[1]); w.w = pkbf(v1[2], v1[3]); if (ok) *(u32x4*)(xb0 + (size_t)r * 1024 + c8) = w; }
;             ss = wave_sum(ss); if (lane == 0 && ok) { ssA[r] = ss; ((float*)(ws + WS_SSQ))[r] = 0.f; } }
.LBB0_985:
	v_mul_f32_e32 v13, v13, v13
	v_mul_f32_e32 v5, v5, v5
	v_fmac_f32_e32 v13, v12, v12
	v_mul_f32_e32 v12, v15, v15
	v_fmac_f32_e32 v5, v4, v4
	v_mul_f32_e32 v4, v7, v7
	v_fmac_f32_e32 v12, v14, v14
	v_mul_f32_e32 v9, v9, v9
	v_fmac_f32_e32 v4, v6, v6
	v_mul_f32_e32 v1, v1, v1
	v_add_f32_e32 v12, v13, v12
	v_fmac_f32_e32 v9, v8, v8
	v_add_f32_e32 v4, v5, v4
	v_fmac_f32_e32 v1, v0, v0
	v_add_f32_e32 v8, v12, v9
	v_mul_f32_e32 v9, v11, v11
	v_add_f32_e32 v0, v4, v1
	v_mul_f32_e32 v1, v3, v3
	v_fmac_f32_e32 v9, v10, v10
	v_fmac_f32_e32 v1, v2, v2
	v_add_f32_e32 v8, v9, v8
	v_add_f32_e32 v0, v1, v0
	v_add_f32_e32 v0, v8, v0
	s_and_b64 s[6:7], s[40:41], s[4:5]
	s_waitcnt lgkmcnt(0)
	s_nop 1
	v_add_f32_dpp v0, v0, v0 quad_perm:[1,0,3,2] row_mask:0xf bank_mask:0xf
	s_waitcnt lgkmcnt(0)
	s_nop 1
	v_add_f32_dpp v0, v0, v0 quad_perm:[2,3,0,1] row_mask:0xf bank_mask:0xf
	s_waitcnt lgkmcnt(0)
	s_nop 1
	v_add_f32_dpp v0, v0, v0 row_half_mirror row_mask:0xf bank_mask:0xf
	s_waitcnt lgkmcnt(0)
	s_nop 1
	v_add_f32_dpp v0, v0, v0 row_mirror row_mask:0xf bank_mask:0xf
	ds_bpermute_b32 v1, v71, v0
	s_waitcnt lgkmcnt(0)
	v_add_f32_e32 v0, v0, v1
	ds_bpermute_b32 v1, v72, v0
	s_and_saveexec_b64 s[4:5], s[6:7]
	s_cbranch_execz .LBB0_978
	s_lshl_b64 s[2:3], s[2:3], 2
	s_add_u32 s6, s18, s2
	s_addc_u32 s7, s19, s3
	s_waitcnt lgkmcnt(0)
	v_add_f32_e32 v0, v0, v1
	s_add_u32 s2, s0, s2
	s_addc_u32 s3, s1, s3
	global_store_dword v133, v0, s[6:7]
	global_store_dword v133, v133, s[2:3]
	s_branch .LBB0_978
